# token-mixer item->workgroup map permuted so each item runs on the XCD that produced/consumes its rows
# speedup vs baseline: 1.0079x; 1.0016x over previous
; __device__ __forceinline__ void p2_block(LAS unsigned char* lds, const bf16_t* __restrict__ PROJ, bf16_t* __restrict__ ATT, bf16_t* __restrict__ SGU, const float* __restrict__ qn, const float* __restrict__ kn, ...
;     ...
;     const int b = item >> 6, n = (item >> 2) & 15, kvh = item & 3;
; __global__ void __launch_bounds__(NTHREADS, 2) mk_fwd(Args args) {
;     ...
;             for (int it = blk; it < 256; it += G) p2_block(lds, PROJ, ATT, SGU, args.in[3] + l * 64, args.in[4] + l * 64, args.in[5] + l * 16, COS, SIN, args.in[6] + l * 1024, args.in[7] + l * 1024,
;                                                            args.in[8] + (size_t)l * 8 * 16384, args.in[9] + l * 1024, it, tid);
.LBB0_326:
	s_andn2_b64 vcc, exec, s[0:1]
	v_readlane_b32 s0, v248, 2
	v_readlane_b32 s1, v248, 3
	s_nop 1
	v_cndmask_b32_e64 v0, 0, 1, s[0:1]
	v_cmp_ne_u32_e64 s[70:71], 1, v0
	s_cbranch_vccnz .LBB0_413
	s_and_b64 vcc, exec, s[70:71]
	s_cbranch_vccnz .LBB0_346
	s_lshl_b32 s4, s64, 6
	v_readlane_b32 s36, v250, 2
	s_lshl_b64 s[0:1], s[4:5], 2
	v_readlane_b32 s38, v250, 4
	v_readlane_b32 s42, v250, 8
	v_readlane_b32 s39, v250, 5
	v_readlane_b32 s43, v250, 9
	s_add_u32 s38, s42, s0
	v_readlane_b32 s44, v250, 10
	s_addc_u32 s39, s43, s1
	v_readlane_b32 s45, v250, 11
	s_add_u32 s0, s44, s0
	s_addc_u32 s1, s45, s1
	s_lshl_b32 s4, s64, 4
	v_readlane_b32 s46, v250, 12
	s_lshl_b64 s[6:7], s[4:5], 2
	v_readlane_b32 s47, v250, 13
	s_add_u32 s63, s46, s6
	s_addc_u32 s78, s47, s7
	s_lshl_b32 s4, s64, 10
	v_readlane_b32 s48, v250, 14
	s_lshl_b64 s[6:7], s[4:5], 2
	v_readlane_b32 s37, v250, 3
	v_readlane_b32 s49, v250, 15
	s_add_u32 s36, s48, s6
	v_readlane_b32 s50, v250, 16
	s_addc_u32 s37, s49, s7
	v_readlane_b32 s40, v250, 6
	v_readlane_b32 s41, v250, 7
	v_readlane_b32 s51, v250, 17
	s_add_u32 s18, s50, s6
	s_addc_u32 s19, s51, s7
	s_lshl_b64 s[16:17], s[64:65], 19
	v_readlane_b32 s40, v250, 18
	v_readlane_b32 s41, v250, 19
	s_add_u32 s20, s40, s16
	v_readlane_b32 s42, v250, 20
	s_addc_u32 s21, s41, s17
	v_readlane_b32 s43, v250, 21
	s_add_u32 s22, s42, s6
	s_addc_u32 s23, s43, s7
	s_and_b32 vcc_lo, s85, 7
	s_lshr_b32 vcc_hi, s85, 3
	s_lshr_b32 s2, vcc_lo, 1
	s_lshl_b32 s2, s2, 6
	s_and_b32 vcc_lo, vcc_lo, 1
	s_lshl_b32 vcc_lo, vcc_lo, 5
	s_or_b32 s2, s2, vcc_lo
	s_lshr_b32 vcc_lo, vcc_hi, 2
	s_lshl_b32 vcc_lo, vcc_lo, 2
	s_or_b32 s2, s2, vcc_lo
	s_and_b32 vcc_hi, vcc_hi, 3
	s_or_b32 s2, s2, vcc_hi
	s_cmpk_eq_u32 s3, 0x100
	s_cselect_b32 s2, s2, s85
	v_readlane_b32 s44, v250, 22
	v_readlane_b32 s45, v250, 23
	v_readlane_b32 s46, v250, 24
	v_readlane_b32 s47, v250, 25
	v_readlane_b32 s48, v250, 26
	v_readlane_b32 s49, v250, 27
	v_readlane_b32 s50, v250, 28
	v_readlane_b32 s51, v250, 29
	v_readlane_b32 s52, v250, 30
	v_readlane_b32 s53, v250, 31
	v_readlane_b32 s54, v250, 32
	v_readlane_b32 s55, v250, 33
	s_branch .LBB0_330
